# v13 plus non-temporal cache policy on the sample units f32 K/V cache loads (streamed once) so they stop evicting the prompt K/V working set
# speedup vs baseline: 1.0074x; 1.0074x over previous
.LBB0_1283:
	v_lshlrev_b32_e32 v120, 11, v140
	v_lshl_add_u64 v[2:3], s[60:61], 0, v[120:121]
	v_mov_b32_e32 v143, v121
	v_lshl_add_u64 v[2:3], v[142:143], 1, v[2:3]
	v_lshlrev_b32_e32 v120, 1, v122
	v_lshl_add_u64 v[2:3], v[2:3], 0, v[120:121]
	v_add_u32_e32 v1, v179, v155
	global_load_dwordx4 v[56:59], v[2:3], off
	global_load_dwordx4 v[60:63], v[2:3], off offset:32
	global_load_dwordx4 v[52:55], v[2:3], off offset:64
	global_load_dwordx4 v[48:51], v[2:3], off offset:96
	v_min_i32_e32 v2, s53, v1
	v_mul_lo_u32 v2, v2, v177
	v_add_u32_e32 v2, v2, v178
	v_add_u32_e32 v3, -8, v2
	v_cmp_lt_i32_e32 vcc, v2, v180
	v_cmp_ne_u32_e64 s[10:11], 0, v0
	v_cmp_eq_u32_e64 s[80:81], 1, v0
	v_cndmask_b32_e32 v2, v3, v2, vcc
	v_ashrrev_i32_e32 v5, 31, v2
	v_mad_u64_u32 v[2:3], s[8:9], v2, v141, 0
	v_mov_b32_e32 v4, v3
	v_mad_u64_u32 v[4:5], s[8:9], v5, v141, v[4:5]
	v_or_b32_e32 v2, v2, v130
	v_mov_b32_e32 v3, v4
	v_cndmask_b32_e32 v5, v145, v149, vcc
	v_cndmask_b32_e32 v4, v144, v148, vcc
	v_lshlrev_b64 v[2:3], 2, v[2:3]
	v_lshl_add_u64 v[4:5], v[4:5], 0, v[2:3]
	global_load_dwordx4 v[112:115], v[4:5], off nt
	v_cndmask_b32_e32 v5, v147, v151, vcc
	v_cndmask_b32_e32 v4, v146, v150, vcc
	v_lshl_add_u64 v[2:3], v[4:5], 0, v[2:3]
	global_load_dwordx4 v[116:119], v[2:3], off nt
	v_add_u32_e32 v2, 4, v1
	v_min_i32_e32 v2, s53, v2
	v_mul_lo_u32 v2, v2, v177
	v_add_u32_e32 v2, v2, v178
	v_add_u32_e32 v3, -8, v2
	v_cmp_lt_i32_e32 vcc, v2, v180
	v_mul_lo_u32 v199, v177, v1
	s_lshl_b32 s51, s18, 5
	v_cndmask_b32_e32 v2, v3, v2, vcc
	v_ashrrev_i32_e32 v5, 31, v2
	v_mad_u64_u32 v[2:3], s[8:9], v2, v141, 0
	v_mov_b32_e32 v4, v3
	v_mad_u64_u32 v[4:5], s[8:9], v5, v141, v[4:5]
	v_or_b32_e32 v2, v2, v130
	v_mov_b32_e32 v3, v4
	v_cndmask_b32_e32 v5, v145, v149, vcc
	v_cndmask_b32_e32 v4, v144, v148, vcc
	v_lshlrev_b64 v[2:3], 2, v[2:3]
	v_lshl_add_u64 v[4:5], v[4:5], 0, v[2:3]
	global_load_dwordx4 v[104:107], v[4:5], off nt
	v_cndmask_b32_e32 v5, v147, v151, vcc
	v_cndmask_b32_e32 v4, v146, v150, vcc
	v_lshl_add_u64 v[2:3], v[4:5], 0, v[2:3]
	global_load_dwordx4 v[108:111], v[2:3], off nt
	v_add_u32_e32 v2, 8, v1
	v_min_i32_e32 v2, s53, v2
	v_mul_lo_u32 v2, v2, v177
	v_add_u32_e32 v2, v2, v178
	v_add_u32_e32 v3, -8, v2
	v_cmp_lt_i32_e32 vcc, v2, v180
	v_lshlrev_b32_e32 v185, 5, v177
	v_mov_b32_e32 v202, 0
	v_cndmask_b32_e32 v2, v3, v2, vcc
	v_ashrrev_i32_e32 v5, 31, v2
	v_mad_u64_u32 v[2:3], s[8:9], v2, v141, 0
	v_mov_b32_e32 v4, v3
	v_mad_u64_u32 v[4:5], s[8:9], v5, v141, v[4:5]
	v_or_b32_e32 v2, v2, v130
	v_mov_b32_e32 v3, v4
	v_cndmask_b32_e32 v5, v145, v149, vcc
	v_cndmask_b32_e32 v4, v144, v148, vcc
	v_lshlrev_b64 v[2:3], 2, v[2:3]
	v_lshl_add_u64 v[4:5], v[4:5], 0, v[2:3]
	global_load_dwordx4 v[96:99], v[4:5], off nt
	v_cndmask_b32_e32 v5, v147, v151, vcc
	v_cndmask_b32_e32 v4, v146, v150, vcc
	v_lshl_add_u64 v[2:3], v[4:5], 0, v[2:3]
	global_load_dwordx4 v[100:103], v[2:3], off nt
	v_add_u32_e32 v2, 12, v1
	v_min_i32_e32 v2, s53, v2
	v_mul_lo_u32 v2, v2, v177
	v_add_u32_e32 v2, v2, v178
	v_add_u32_e32 v3, -8, v2
	v_cmp_lt_i32_e32 vcc, v2, v180
	s_mov_b32 s33, 0
	s_add_i32 s48, s53, -4
	v_cndmask_b32_e32 v2, v3, v2, vcc
	v_ashrrev_i32_e32 v5, 31, v2
	v_mad_u64_u32 v[2:3], s[8:9], v2, v141, 0
	v_mov_b32_e32 v4, v3
	v_mad_u64_u32 v[4:5], s[8:9], v5, v141, v[4:5]
	v_or_b32_e32 v2, v2, v130
	v_mov_b32_e32 v3, v4
	v_cndmask_b32_e32 v5, v145, v149, vcc
	v_cndmask_b32_e32 v4, v144, v148, vcc
	v_lshlrev_b64 v[2:3], 2, v[2:3]
	v_lshl_add_u64 v[4:5], v[4:5], 0, v[2:3]
	global_load_dwordx4 v[88:91], v[4:5], off nt
	v_cndmask_b32_e32 v5, v147, v151, vcc
	v_cndmask_b32_e32 v4, v146, v150, vcc
	v_lshl_add_u64 v[2:3], v[4:5], 0, v[2:3]
	global_load_dwordx4 v[92:95], v[2:3], off nt
	v_add_u32_e32 v2, 16, v1
	v_min_i32_e32 v2, s53, v2
	v_mul_lo_u32 v2, v2, v177
	v_add_u32_e32 v2, v2, v178
	v_add_u32_e32 v3, -8, v2
	v_cmp_lt_i32_e32 vcc, v2, v180
	s_add_i32 s49, s53, -8
	s_add_i32 s56, s53, -12
	v_cndmask_b32_e32 v2, v3, v2, vcc
	v_ashrrev_i32_e32 v5, 31, v2
	v_mad_u64_u32 v[2:3], s[8:9], v2, v141, 0
	v_mov_b32_e32 v4, v3
	v_mad_u64_u32 v[4:5], s[8:9], v5, v141, v[4:5]
	v_or_b32_e32 v2, v2, v130
	v_mov_b32_e32 v3, v4
	v_cndmask_b32_e32 v5, v145, v149, vcc
	v_cndmask_b32_e32 v4, v144, v148, vcc
	v_lshlrev_b64 v[2:3], 2, v[2:3]
	v_lshl_add_u64 v[4:5], v[4:5], 0, v[2:3]
	global_load_dwordx4 v[80:83], v[4:5], off nt
	v_cndmask_b32_e32 v5, v147, v151, vcc
	v_cndmask_b32_e32 v4, v146, v150, vcc
	v_lshl_add_u64 v[2:3], v[4:5], 0, v[2:3]
	global_load_dwordx4 v[84:87], v[2:3], off nt
	v_add_u32_e32 v2, 20, v1
	v_min_i32_e32 v2, s53, v2
	v_mul_lo_u32 v2, v2, v177
	v_add_u32_e32 v2, v2, v178
	v_add_u32_e32 v3, -8, v2
	v_cmp_lt_i32_e32 vcc, v2, v180
	s_add_i32 s42, s53, -16
	s_sub_i32 s54, s53, 20
	v_cndmask_b32_e32 v2, v3, v2, vcc
	v_ashrrev_i32_e32 v5, 31, v2
	v_mad_u64_u32 v[2:3], s[8:9], v2, v141, 0
	v_mov_b32_e32 v4, v3
	v_mad_u64_u32 v[4:5], s[8:9], v5, v141, v[4:5]
	v_or_b32_e32 v2, v2, v130
	v_mov_b32_e32 v3, v4
	v_cndmask_b32_e32 v5, v145, v149, vcc
	v_cndmask_b32_e32 v4, v144, v148, vcc
	v_lshlrev_b64 v[2:3], 2, v[2:3]
	v_lshl_add_u64 v[4:5], v[4:5], 0, v[2:3]
	global_load_dwordx4 v[64:67], v[4:5], off nt
	v_cndmask_b32_e32 v5, v147, v151, vcc
	v_cndmask_b32_e32 v4, v146, v150, vcc
	v_lshl_add_u64 v[2:3], v[4:5], 0, v[2:3]
	global_load_dwordx4 v[68:71], v[2:3], off nt
	v_add_u32_e32 v2, 24, v1
	v_min_i32_e32 v2, s53, v2
	v_mul_lo_u32 v2, v2, v177
	v_add_u32_e32 v2, v2, v178
	v_add_u32_e32 v3, -8, v2
	v_cmp_lt_i32_e32 vcc, v2, v180
	s_sub_i32 s50, s53, 24
	s_sub_i32 s34, s53, 28
	v_cndmask_b32_e32 v2, v3, v2, vcc
	v_ashrrev_i32_e32 v5, 31, v2
	v_mad_u64_u32 v[2:3], s[8:9], v2, v141, 0
	v_mov_b32_e32 v4, v3
	v_mad_u64_u32 v[4:5], s[8:9], v5, v141, v[4:5]
	v_or_b32_e32 v2, v2, v130
	v_mov_b32_e32 v3, v4
	v_cndmask_b32_e32 v5, v145, v149, vcc
	v_cndmask_b32_e32 v4, v144, v148, vcc
	v_lshlrev_b64 v[2:3], 2, v[2:3]
	v_lshl_add_u64 v[4:5], v[4:5], 0, v[2:3]
	global_load_dwordx4 v[72:75], v[4:5], off nt
	v_cndmask_b32_e32 v5, v147, v151, vcc
	v_cndmask_b32_e32 v4, v146, v150, vcc
	v_lshl_add_u64 v[2:3], v[4:5], 0, v[2:3]
	global_load_dwordx4 v[76:79], v[2:3], off nt
	v_add_u32_e32 v2, 28, v1
	v_min_i32_e32 v2, s53, v2
	v_mul_lo_u32 v2, v2, v177
	v_add_u32_e32 v2, v2, v178
	v_add_u32_e32 v3, -8, v2
	v_cmp_lt_i32_e32 vcc, v2, v180
	s_add_i32 s18, s51, 32
	v_add_u32_e32 v182, v159, v179
	v_cndmask_b32_e32 v2, v3, v2, vcc
	v_ashrrev_i32_e32 v5, 31, v2
	v_mad_u64_u32 v[2:3], s[8:9], v2, v141, 0
	v_mov_b32_e32 v4, v3
	v_mad_u64_u32 v[4:5], s[8:9], v5, v141, v[4:5]
	v_or_b32_e32 v2, v2, v130
	v_mov_b32_e32 v3, v4
	v_cndmask_b32_e32 v5, v145, v149, vcc
	v_cndmask_b32_e32 v4, v144, v148, vcc
	v_lshlrev_b64 v[2:3], 2, v[2:3]
	v_lshl_add_u64 v[4:5], v[4:5], 0, v[2:3]
	global_load_dwordx4 v[32:35], v[4:5], off nt
	v_cndmask_b32_e32 v5, v147, v151, vcc
	v_cndmask_b32_e32 v4, v146, v150, vcc
	v_lshl_add_u64 v[2:3], v[4:5], 0, v[2:3]
	global_load_dwordx4 v[36:39], v[2:3], off nt
	v_and_b32_e32 v3, 64, v128
	v_xor_b32_e32 v2, 32, v128
	v_add_u32_e32 v3, 64, v3
	v_cmp_lt_i32_e32 vcc, v2, v3
	v_cmp_ne_u32_e64 s[8:9], 1, v0
	v_add_u32_e32 v0, v158, v139
	v_cndmask_b32_e32 v2, v128, v2, vcc
	v_lshlrev_b32_e32 v143, 2, v2
	v_add_u32_e32 v2, v160, v179
	v_sub_u32_e32 v181, v0, v179
	v_add_u32_e32 v0, -8, v178
	v_mul_lo_u32 v183, v177, v2
	v_add_u32_e32 v2, v0, v183
	v_mul_lo_u32 v184, v141, v2
	v_add_u32_e32 v2, v161, v179
	v_mul_lo_u32 v187, v177, v2
	v_add_u32_e32 v2, v0, v187
	v_mul_lo_u32 v188, v141, v2
	v_add_u32_e32 v2, v162, v179
	v_mul_lo_u32 v189, v177, v2
	v_add_u32_e32 v2, v0, v189
	v_mul_lo_u32 v190, v141, v2
	v_add_u32_e32 v2, v163, v179
	v_mul_lo_u32 v191, v177, v2
	v_add_u32_e32 v2, v0, v191
	v_mul_lo_u32 v192, v141, v2
	v_add_u32_e32 v2, v167, v179
	v_mul_lo_u32 v193, v177, v2
	v_add_u32_e32 v2, v0, v193
	v_mul_lo_u32 v194, v141, v2
	v_add_u32_e32 v2, v168, v179
	v_mul_lo_u32 v195, v177, v2
	v_add_u32_e32 v2, v0, v195
	v_mul_lo_u32 v196, v141, v2
	v_add_u32_e32 v2, v169, v179
	v_mul_lo_u32 v197, v177, v2
	v_add_u32_e32 v2, v0, v197
	v_add_u32_e32 v0, v0, v199
	v_mul_lo_u32 v186, v185, v141
	v_mul_lo_u32 v198, v141, v2
	v_mul_lo_u32 v200, v141, v0
	v_mov_b32_e32 v208, 0xf149f2ca
	v_mov_b32_e32 v201, v178
	v_mov_b32_e32 v16, 0
	v_mov_b32_e32 v17, v202
	v_mov_b32_e32 v18, v202
	v_mov_b32_e32 v19, v202
	v_mov_b32_e32 v20, v202
	v_mov_b32_e32 v21, v202
	v_mov_b32_e32 v22, v202
	v_mov_b32_e32 v23, v202
	v_mov_b32_e32 v24, v202
	v_mov_b32_e32 v25, v202
	v_mov_b32_e32 v26, v202
	v_mov_b32_e32 v27, v202
	v_mov_b32_e32 v28, v202
	v_mov_b32_e32 v29, v202
	v_mov_b32_e32 v30, v202
	v_mov_b32_e32 v31, v202
	v_mov_b32_e32 v0, 0
	v_mov_b32_e32 v1, v202
	v_mov_b32_e32 v2, v202
	v_mov_b32_e32 v3, v202
	v_mov_b32_e32 v4, v202
	v_mov_b32_e32 v5, v202
	v_mov_b32_e32 v6, v202
	v_mov_b32_e32 v7, v202
	v_mov_b32_e32 v8, v202
	v_mov_b32_e32 v9, v202
	v_mov_b32_e32 v10, v202
	v_mov_b32_e32 v11, v202
	v_mov_b32_e32 v12, v202
	v_mov_b32_e32 v13, v202
	v_mov_b32_e32 v14, v202
	v_mov_b32_e32 v15, v202

.LBB0_1326:
	v_subrev_u32_e32 v32, 28, v182
	v_min_i32_e32 v32, s53, v32
	v_mul_lo_u32 v32, v32, v177
	v_add_u32_e32 v32, v32, v178
	v_add_u32_e32 v33, -8, v32
	v_cmp_lt_i32_e32 vcc, v32, v180
	v_add_u32_e32 v211, v127, v129
	ds_read_b128 v[216:219], v211 offset:64
	v_cndmask_b32_e32 v32, v33, v32, vcc
	v_ashrrev_i32_e32 v35, 31, v32
	v_mad_u64_u32 v[32:33], s[16:17], v32, v141, 0
	v_mov_b32_e32 v34, v33
	v_mad_u64_u32 v[34:35], s[16:17], v35, v141, v[34:35]
	v_or_b32_e32 v32, v32, v130
	v_mov_b32_e32 v33, v34
	v_cndmask_b32_e32 v35, v145, v149, vcc
	v_cndmask_b32_e32 v34, v144, v148, vcc
	v_lshlrev_b64 v[32:33], 2, v[32:33]
	v_lshl_add_u64 v[34:35], v[34:35], 0, v[32:33]
	global_load_dwordx4 v[112:115], v[34:35], off nt
	v_cndmask_b32_e32 v35, v147, v151, vcc
	v_cndmask_b32_e32 v34, v146, v150, vcc
	v_lshl_add_u64 v[32:33], v[34:35], 0, v[32:33]
	global_load_dwordx4 v[116:119], v[32:33], off nt
	v_subrev_u32_e32 v32, 24, v182
	v_min_i32_e32 v32, s53, v32
	v_mul_lo_u32 v32, v32, v177
	v_add_u32_e32 v32, v32, v178
	v_add_u32_e32 v33, -8, v32
	v_cmp_lt_i32_e32 vcc, v32, v180
	v_min_i32_e32 v120, s53, v182
	v_mul_lo_u32 v120, v120, v177
	v_cndmask_b32_e32 v32, v33, v32, vcc
	v_ashrrev_i32_e32 v35, 31, v32
	v_mad_u64_u32 v[32:33], s[16:17], v32, v141, 0
	v_mov_b32_e32 v34, v33
	v_mad_u64_u32 v[34:35], s[16:17], v35, v141, v[34:35]
	v_or_b32_e32 v32, v32, v130
	v_mov_b32_e32 v33, v34
	v_cndmask_b32_e32 v35, v145, v149, vcc
	v_cndmask_b32_e32 v34, v144, v148, vcc
	v_lshlrev_b64 v[32:33], 2, v[32:33]
	v_lshl_add_u64 v[34:35], v[34:35], 0, v[32:33]
	global_load_dwordx4 v[104:107], v[34:35], off nt
	v_cndmask_b32_e32 v35, v147, v151, vcc
	v_cndmask_b32_e32 v34, v146, v150, vcc
	v_lshl_add_u64 v[32:33], v[34:35], 0, v[32:33]
	global_load_dwordx4 v[108:111], v[32:33], off nt
	v_subrev_u32_e32 v32, 20, v182
	v_min_i32_e32 v32, s53, v32
	v_mul_lo_u32 v32, v32, v177
	v_add_u32_e32 v32, v32, v178
	v_add_u32_e32 v33, -8, v32
	v_cmp_lt_i32_e32 vcc, v32, v180
	v_add_u32_e32 v120, v120, v178
	v_add_u32_e32 v209, -8, v120
	v_cndmask_b32_e32 v32, v33, v32, vcc
	v_ashrrev_i32_e32 v35, 31, v32
	v_mad_u64_u32 v[32:33], s[16:17], v32, v141, 0
	v_mov_b32_e32 v34, v33
	v_mad_u64_u32 v[34:35], s[16:17], v35, v141, v[34:35]
	v_or_b32_e32 v32, v32, v130
	v_mov_b32_e32 v33, v34
	v_cndmask_b32_e32 v35, v145, v149, vcc
	v_cndmask_b32_e32 v34, v144, v148, vcc
	v_lshlrev_b64 v[32:33], 2, v[32:33]
	v_lshl_add_u64 v[34:35], v[34:35], 0, v[32:33]
	global_load_dwordx4 v[96:99], v[34:35], off nt
	v_cndmask_b32_e32 v35, v147, v151, vcc
	v_cndmask_b32_e32 v34, v146, v150, vcc
	v_lshl_add_u64 v[32:33], v[34:35], 0, v[32:33]
	global_load_dwordx4 v[100:103], v[32:33], off nt
	v_add_u32_e32 v32, -16, v182
	v_min_i32_e32 v32, s53, v32
	v_mul_lo_u32 v32, v32, v177
	v_add_u32_e32 v32, v32, v178
	v_add_u32_e32 v33, -8, v32
	v_cmp_lt_i32_e32 vcc, v32, v180
	v_add_u32_e32 v184, v184, v186
	v_add_u32_e32 v201, v201, v185
	v_cndmask_b32_e32 v32, v33, v32, vcc
	v_ashrrev_i32_e32 v35, 31, v32
	v_mad_u64_u32 v[32:33], s[16:17], v32, v141, 0
	v_mov_b32_e32 v34, v33
	v_mad_u64_u32 v[34:35], s[16:17], v35, v141, v[34:35]
	v_or_b32_e32 v32, v32, v130
	v_mov_b32_e32 v33, v34
	v_cndmask_b32_e32 v35, v145, v149, vcc
	v_cndmask_b32_e32 v34, v144, v148, vcc
	v_lshlrev_b64 v[32:33], 2, v[32:33]
	v_lshl_add_u64 v[34:35], v[34:35], 0, v[32:33]
	global_load_dwordx4 v[88:91], v[34:35], off nt
	v_cndmask_b32_e32 v35, v147, v151, vcc
	v_cndmask_b32_e32 v34, v146, v150, vcc
	v_lshl_add_u64 v[32:33], v[34:35], 0, v[32:33]
	global_load_dwordx4 v[92:95], v[32:33], off nt
	v_add_u32_e32 v32, -12, v182
	v_min_i32_e32 v32, s53, v32
	v_mul_lo_u32 v32, v32, v177
	v_add_u32_e32 v32, v32, v178
	v_add_u32_e32 v33, -8, v32
	v_cmp_lt_i32_e32 vcc, v32, v180
	ds_read_b128 v[212:215], v211 offset:32
	v_add_u32_e32 v188, v188, v186
	v_cndmask_b32_e32 v32, v33, v32, vcc
	v_ashrrev_i32_e32 v35, 31, v32
	v_mad_u64_u32 v[32:33], s[16:17], v32, v141, 0
	v_mov_b32_e32 v34, v33
	v_mad_u64_u32 v[34:35], s[16:17], v35, v141, v[34:35]
	v_or_b32_e32 v32, v32, v130
	v_mov_b32_e32 v33, v34
	v_cndmask_b32_e32 v35, v145, v149, vcc
	v_cndmask_b32_e32 v34, v144, v148, vcc
	v_lshlrev_b64 v[32:33], 2, v[32:33]
	v_lshl_add_u64 v[34:35], v[34:35], 0, v[32:33]
	global_load_dwordx4 v[80:83], v[34:35], off nt
	v_cndmask_b32_e32 v35, v147, v151, vcc
	v_cndmask_b32_e32 v34, v146, v150, vcc
	v_lshl_add_u64 v[32:33], v[34:35], 0, v[32:33]
	global_load_dwordx4 v[84:87], v[32:33], off nt
	v_add_u32_e32 v32, -8, v182
	v_min_i32_e32 v32, s53, v32
	v_mul_lo_u32 v32, v32, v177
	v_add_u32_e32 v32, v32, v178
	v_add_u32_e32 v33, -8, v32
	v_cmp_lt_i32_e32 vcc, v32, v180
	v_add_u32_e32 v190, v190, v186
	v_add_u32_e32 v192, v192, v186
	v_cndmask_b32_e32 v32, v33, v32, vcc
	v_ashrrev_i32_e32 v35, 31, v32
	v_mad_u64_u32 v[32:33], s[16:17], v32, v141, 0
	v_mov_b32_e32 v34, v33
	v_mad_u64_u32 v[34:35], s[16:17], v35, v141, v[34:35]
	v_or_b32_e32 v32, v32, v130
	v_mov_b32_e32 v33, v34
	v_cndmask_b32_e32 v35, v145, v149, vcc
	v_cndmask_b32_e32 v34, v144, v148, vcc
	v_lshlrev_b64 v[32:33], 2, v[32:33]
	v_lshl_add_u64 v[34:35], v[34:35], 0, v[32:33]
	global_load_dwordx4 v[64:67], v[34:35], off nt
	v_cndmask_b32_e32 v35, v147, v151, vcc
	v_cndmask_b32_e32 v34, v146, v150, vcc
	v_lshl_add_u64 v[32:33], v[34:35], 0, v[32:33]
	global_load_dwordx4 v[68:71], v[32:33], off nt
	v_add_u32_e32 v32, -4, v182
	v_min_i32_e32 v32, s53, v32
	v_mul_lo_u32 v32, v32, v177
	v_add_u32_e32 v32, v32, v178
	v_add_u32_e32 v33, -8, v32
	v_cmp_lt_i32_e32 vcc, v32, v180
	v_add_u32_e32 v182, 32, v182
	v_add_u32_e32 v194, v194, v186
	v_cndmask_b32_e32 v32, v33, v32, vcc
	v_ashrrev_i32_e32 v35, 31, v32
	v_mad_u64_u32 v[32:33], s[16:17], v32, v141, 0
	v_mov_b32_e32 v34, v33
	v_mad_u64_u32 v[34:35], s[16:17], v35, v141, v[34:35]
	v_or_b32_e32 v36, v32, v130
	v_mov_b32_e32 v37, v34
	ds_read_b128 v[32:35], v211
	v_cndmask_b32_e32 v39, v145, v149, vcc
	v_cndmask_b32_e32 v38, v144, v148, vcc
	v_lshlrev_b64 v[76:77], 2, v[36:37]
	v_lshl_add_u64 v[36:37], v[38:39], 0, v[76:77]
	global_load_dwordx4 v[72:75], v[36:37], off nt
	s_waitcnt lgkmcnt(0)
	v_mfma_f32_32x32x16_bf16 v[32:47], v[32:35], v[56:59], 0
	v_cndmask_b32_e32 v79, v147, v151, vcc
	v_cndmask_b32_e32 v78, v146, v150, vcc
	v_cmp_lt_i32_e32 vcc, v120, v180
	v_lshl_add_u64 v[76:77], v[78:79], 0, v[76:77]
	global_load_dwordx4 v[76:79], v[76:77], off nt
	v_cndmask_b32_e32 v120, v209, v120, vcc
	v_mad_u64_u32 v[220:221], s[16:17], v120, v141, 0
	v_mfma_f32_32x32x16_bf16 v[32:47], v[212:215], v[60:63], v[32:47]
	ds_read_b128 v[212:215], v211 offset:96
	v_ashrrev_i32_e32 v209, 31, v120
	v_mov_b32_e32 v120, v221
	v_add_u32_e32 v196, v196, v186
	v_add_u32_e32 v198, v198, v186
	v_add_u32_e32 v200, v200, v186
	v_mfma_f32_32x32x16_bf16 v[32:47], v[216:219], v[52:55], v[32:47]
	v_mad_u64_u32 v[216:217], s[16:17], v209, v141, v[120:121]
	v_add_u32_e32 v120, s33, v181
	v_cmp_le_u32_e64 s[16:17], v120, v135
	v_or_b32_e32 v218, v220, v130
	v_mov_b32_e32 v219, v216
	v_cndmask_b32_e32 v217, v145, v149, vcc
	s_waitcnt lgkmcnt(0)
	v_mfma_f32_32x32x16_bf16 v[32:47], v[212:215], v[48:51], v[32:47]
	v_cndmask_b32_e32 v216, v144, v148, vcc
	v_lshlrev_b64 v[218:219], 2, v[218:219]
	s_sub_i32 s33, s33, 32
	s_nop 8
	v_cndmask_b32_e64 v210, v173, v32, s[16:17]
	v_add_u32_e32 v32, -1, v120
	v_cmp_le_u32_e64 s[16:17], v32, v135
	s_nop 1
	v_cndmask_b32_e64 v212, v173, v33, s[16:17]
	v_add_u32_e32 v33, -2, v120
	v_cmp_le_u32_e64 s[16:17], v33, v135
	v_add_u32_e32 v33, -3, v120
	v_max3_f32 v32, v210, s90, v212
	v_cndmask_b32_e64 v213, v173, v34, s[16:17]
	v_cmp_le_u32_e64 s[16:17], v33, v135
	v_add_u32_e32 v33, -8, v120
	s_nop 0
	v_cndmask_b32_e64 v214, v173, v35, s[16:17]
	v_cmp_le_u32_e64 s[16:17], v33, v135
	v_add_u32_e32 v33, -9, v120
	v_max3_f32 v32, v32, v213, v214
	v_cndmask_b32_e64 v215, v173, v36, s[16:17]
	v_cmp_le_u32_e64 s[16:17], v33, v135
	v_add_u32_e32 v33, -10, v120
	v_cndmask_b32_e32 v36, v146, v150, vcc
	v_cndmask_b32_e64 v220, v173, v37, s[16:17]
	v_cmp_le_u32_e64 s[16:17], v33, v135
	v_add_u32_e32 v33, -11, v120
	v_max3_f32 v32, v32, v215, v220
	v_cndmask_b32_e64 v221, v173, v38, s[16:17]
	v_cmp_le_u32_e64 s[16:17], v33, v135
	v_add_u32_e32 v33, -16, v120
	v_cndmask_b32_e32 v37, v147, v151, vcc
	v_cndmask_b32_e64 v222, v173, v39, s[16:17]
	v_cmp_le_u32_e64 s[16:17], v33, v135
	v_subrev_u32_e32 v33, 17, v120
	v_max3_f32 v32, v32, v221, v222
	v_cndmask_b32_e64 v40, v173, v40, s[16:17]
	v_cmp_le_u32_e64 s[16:17], v33, v135
	v_subrev_u32_e32 v33, 18, v120
	v_lshl_add_u64 v[36:37], v[36:37], 0, v[218:219]
	v_cndmask_b32_e64 v41, v173, v41, s[16:17]
	v_cmp_le_u32_e64 s[16:17], v33, v135
	v_subrev_u32_e32 v33, 19, v120
	v_max3_f32 v32, v32, v40, v41
	v_cndmask_b32_e64 v42, v173, v42, s[16:17]
	v_cmp_le_u32_e64 s[16:17], v33, v135
	v_subrev_u32_e32 v33, 24, v120
	s_nop 0
	v_cndmask_b32_e64 v43, v173, v43, s[16:17]
	v_cmp_le_u32_e64 s[16:17], v33, v135
	v_subrev_u32_e32 v33, 25, v120
	v_max3_f32 v32, v32, v42, v43
	v_cndmask_b32_e64 v44, v173, v44, s[16:17]
	v_cmp_le_u32_e64 s[16:17], v33, v135
	v_subrev_u32_e32 v33, 26, v120
	s_nop 0
	v_cndmask_b32_e64 v45, v173, v45, s[16:17]
	v_cmp_le_u32_e64 s[16:17], v33, v135
	v_subrev_u32_e32 v33, 27, v120
	v_max3_f32 v32, v32, v44, v45
	v_cndmask_b32_e64 v46, v173, v46, s[16:17]
	v_cmp_le_u32_e64 s[16:17], v33, v135
	s_nop 1
	v_cndmask_b32_e64 v47, v173, v47, s[16:17]
	v_max3_f32 v38, v32, v46, v47
	ds_bpermute_b32 v39, v143, v38
	v_lshl_add_u64 v[32:33], v[216:217], 0, v[218:219]
	global_load_dwordx4 v[32:35], v[32:33], off nt
	s_add_i32 s16, s18, s33
	s_cmp_lg_u32 s16, 0
	s_waitcnt lgkmcnt(0)
	v_max3_f32 v209, v208, v38, v39
	v_sub_f32_e32 v38, v210, v209
	v_exp_f32_e32 v210, v38
	global_load_dwordx4 v[36:39], v[36:37], off nt
	v_sub_f32_e32 v212, v212, v209
	v_exp_f32_e32 v212, v212
	v_sub_f32_e32 v213, v213, v209
	v_exp_f32_e32 v213, v213
	v_sub_f32_e32 v214, v214, v209
	v_exp_f32_e32 v214, v214
	v_sub_f32_e32 v215, v215, v209
	v_sub_f32_e32 v120, v208, v209
	v_add_f32_e32 v208, 0, v210
	v_exp_f32_e32 v215, v215
	v_sub_f32_e32 v216, v220, v209
	v_add_f32_e32 v208, v212, v208
	v_exp_f32_e32 v216, v216
	v_sub_f32_e32 v217, v221, v209
	v_add_f32_e32 v208, v213, v208
	v_exp_f32_e32 v217, v217
	v_sub_f32_e32 v218, v222, v209
	v_add_f32_e32 v208, v214, v208
	v_exp_f32_e32 v218, v218
	v_sub_f32_e32 v40, v40, v209
	v_add_f32_e32 v208, v215, v208
	v_exp_f32_e32 v220, v40
	v_sub_f32_e32 v41, v41, v209
	v_add_f32_e32 v40, v216, v208
	v_exp_f32_e32 v208, v41
	v_sub_f32_e32 v41, v42, v209
	v_add_f32_e32 v40, v217, v40
	v_exp_f32_e32 v221, v41
	v_sub_f32_e32 v41, v43, v209
	v_add_f32_e32 v40, v218, v40
	v_exp_f32_e32 v222, v41
	v_sub_f32_e32 v41, v44, v209
	v_add_f32_e32 v40, v220, v40
	v_exp_f32_e32 v223, v41
	v_sub_f32_e32 v41, v45, v209
	v_add_f32_e32 v40, v208, v40
	v_exp_f32_e32 v224, v41
	v_sub_f32_e32 v41, v46, v209
	v_add_f32_e32 v40, v221, v40
	v_exp_f32_e32 v225, v41
	v_sub_f32_e32 v41, v47, v209
	v_add_f32_e32 v40, v222, v40
	v_exp_f32_e32 v226, v41
	v_add_f32_e32 v40, v223, v40
	v_add_f32_e32 v40, v224, v40
	v_add_f32_e32 v40, v225, v40
	v_exp_f32_e32 v120, v120
	v_add_f32_e32 v227, v226, v40
	ds_read_b64_tr_b16 v[40:41], v175 offset:4608
	ds_read_b64_tr_b16 v[42:43], v175 offset:5760
	v_cvt_pk_bf16_f32 v44, v210, v212
	v_cvt_pk_bf16_f32 v45, v213, v214
	v_cvt_pk_bf16_f32 v46, v215, v216
	v_cvt_pk_bf16_f32 v47, v217, v218
	ds_read_b64_tr_b16 v[212:213], v175 offset:6912
	ds_read_b64_tr_b16 v[214:215], v175 offset:8064
	ds_read_b64_tr_b16 v[218:219], v175 offset:5824
	ds_read_b64_tr_b16 v[216:217], v175 offset:4672
	v_pk_mul_f32 v[14:15], v[14:15], v[120:121] op_sel_hi:[1,0]
	v_pk_mul_f32 v[12:13], v[12:13], v[120:121] op_sel_hi:[1,0]
	v_pk_mul_f32 v[10:11], v[10:11], v[120:121] op_sel_hi:[1,0]
	v_pk_mul_f32 v[8:9], v[8:9], v[120:121] op_sel_hi:[1,0]
	v_pk_mul_f32 v[6:7], v[6:7], v[120:121] op_sel_hi:[1,0]
	v_pk_mul_f32 v[4:5], v[4:5], v[120:121] op_sel_hi:[1,0]
	v_pk_mul_f32 v[2:3], v[2:3], v[120:121] op_sel_hi:[1,0]
	v_pk_mul_f32 v[0:1], v[0:1], v[120:121] op_sel_hi:[1,0]
	v_pk_mul_f32 v[30:31], v[30:31], v[120:121] op_sel_hi:[1,0]
	v_pk_mul_f32 v[28:29], v[28:29], v[120:121] op_sel_hi:[1,0]
	v_pk_mul_f32 v[26:27], v[26:27], v[120:121] op_sel_hi:[1,0]
	v_pk_mul_f32 v[24:25], v[24:25], v[120:121] op_sel_hi:[1,0]
	v_pk_mul_f32 v[22:23], v[22:23], v[120:121] op_sel_hi:[1,0]
	v_pk_mul_f32 v[20:21], v[20:21], v[120:121] op_sel_hi:[1,0]
	v_pk_mul_f32 v[18:19], v[18:19], v[120:121] op_sel_hi:[1,0]
	v_pk_mul_f32 v[16:17], v[16:17], v[120:121] op_sel_hi:[1,0]
	s_waitcnt lgkmcnt(4)
	v_mfma_f32_32x32x16_bf16 v[0:15], v[40:43], v[44:47], v[0:15]
	v_cvt_pk_bf16_f32 v40, v220, v208
	v_cvt_pk_bf16_f32 v41, v221, v222
	v_cvt_pk_bf16_f32 v42, v223, v224
	ds_read_b64_tr_b16 v[222:223], v175 offset:8128
	ds_read_b64_tr_b16 v[220:221], v175 offset:6976
	v_cvt_pk_bf16_f32 v43, v225, v226
	s_waitcnt lgkmcnt(2)
	v_mfma_f32_32x32x16_bf16 v[16:31], v[216:219], v[44:47], v[16:31]
	ds_bpermute_b32 v44, v143, v227
	s_waitcnt lgkmcnt(0)
	v_add_f32_e32 v210, v227, v44
	v_fmac_f32_e32 v210, v202, v120
	v_mfma_f32_32x32x16_bf16 v[0:15], v[212:215], v[40:43], v[0:15]
	v_mfma_f32_32x32x16_bf16 v[16:31], v[220:223], v[40:43], v[16:31]
	s_cbranch_scc0 .LBB0_1328
	v_mov_b32_e32 v208, v209
	v_mov_b32_e32 v202, v210
	s_branch .LBB0_1284
